# sample-row split-K GEMM, SwiGLU instances: all 24 fragments of a wave's 8 K-steps requested up front (straight line instead of two loop trips)
# baseline (speedup 1.0000x reference)
; template <int MODE>
; __device__ __forceinline__ void small_gemm(LAS unsigned char* lds, const bf16* A, const bf16* Bt, int N, int K, bf16* O, int ldc, int act_cols, const float* bias, const bf16* Yv, int ldy, int it0, int it1) {
;     ...
;     for (int it = it0; it < it1; ++it) {
;         const int item = BX + it * GSZ; if (item >= nitems) break;
;         const int rt = item & 3, ct = item >> 2;
;         const int hc = 32 * ct + tl;
;         const int brow = (MODE == 3) ? (256 * (hc >> 7) + (hc & 127)) : hc;
;         const bf16* ap = A + (size_t)(32 * rt + tl) * K + wave * kw + 8 * hh;
;         const bf16* bp = Bt + (size_t)brow * K + wave * kw + 8 * hh;
;         v16f acc0, acc1;
; #pragma unroll
;         for (int r = 0; r < 16; ++r) { acc0[r] = 0.f; acc1[r] = 0.f; }
; #pragma unroll 4
;         for (int ks = 0; ks < nks; ++ks) {
;             const bfx8 a = *(const bfx8*)(ap + 16 * ks);
;             const bfx8 b0 = *(const bfx8*)(bp + 16 * ks);
;             acc0 = __builtin_amdgcn_mfma_f32_32x32x16_bf16(b0, a, acc0, 0, 0, 0);
;             if (MODE == 3) { const bfx8 b1 = *(const bfx8*)(bp + (size_t)128 * K + 16 * ks); acc1 = __builtin_amdgcn_mfma_f32_32x32x16_bf16(b1, a, acc1, 0, 0, 0); }
;         }
;         __syncthreads();
; #pragma unroll
;         for (int r = 0; r < 16; ++r) { red[(wave * 16 + r) * 64 + lane] = acc0[r]; if (MODE == 3) red[8192 + (wave * 16 + r) * 64 + lane] = acc1[r]; }
;         __syncthreads();
;         float v0[2], v1[2];
; #pragma unroll
;         for (int e = 0; e < 2; ++e) { float s0 = 0.f, s1 = 0.f;
; #pragma unroll
;             for (int w = 0; w < 8; ++w) { s0 += red[(w * 16 + 2 * wave + e) * 64 + lane]; if (MODE == 3) s1 += red[8192 + (w * 16 + 2 * wave + e) * 64 + lane]; }
;             v0[e] = s0; v1[e] = s1; }
;         const int reg = 2 * wave;
;         const int col = 32 * ct + (reg & 3) + 8 * (reg >> 2) + 4 * hh;
;         const size_t row = (size_t)(32 * rt + tl);
;         float o0 = v0[0], o1 = v0[1];
;         if (MODE == 1) { if (col < act_cols) { o0 = gelu_t(o0); o1 = gelu_t(o1); } }
;         if (MODE == 2) { const unsigned y = *(const unsigned*)(Yv + row * ldy + col); o0 = bf_lo(y) * pg8::sigmoid_f(o0 + bias[col]); o1 = bf_hi(y) * pg8::sigmoid_f(o1 + bias[col + 1]); }
;         if (MODE == 3) { o0 = pg8::silu_f(o0) * v1[0]; o1 = pg8::silu_f(o1) * v1[1]; }
.LBB0_201:
	v_add_co_u32_e32 v76, vcc, s13, v38
	s_nop 1
	v_addc_co_u32_e32 v77, vcc, 0, v39, vcc
	v_add_co_u32_e32 v78, vcc, s14, v38
	s_nop 1
	v_addc_co_u32_e32 v79, vcc, 0, v39, vcc
	global_load_dwordx4 v[80:83], v[40:41], off offset:-64
	global_load_dwordx4 v[84:87], v[76:77], off
	global_load_dwordx4 v[88:91], v[78:79], off
	global_load_dwordx4 v[92:95], v[40:41], off offset:-32
	global_load_dwordx4 v[96:99], v[76:77], off offset:32
	global_load_dwordx4 v[100:103], v[78:79], off offset:32
	global_load_dwordx4 v[104:107], v[40:41], off
	global_load_dwordx4 v[108:111], v[76:77], off offset:64
	global_load_dwordx4 v[112:115], v[78:79], off offset:64
	global_load_dwordx4 v[116:119], v[40:41], off offset:32
	global_load_dwordx4 v[120:123], v[76:77], off offset:96
	global_load_dwordx4 v[124:127], v[78:79], off offset:96
	global_load_dwordx4 v[128:131], v[40:41], off offset:64
	global_load_dwordx4 v[132:135], v[76:77], off offset:128
	global_load_dwordx4 v[136:139], v[78:79], off offset:128
	global_load_dwordx4 v[140:143], v[40:41], off offset:96
	global_load_dwordx4 v[144:147], v[76:77], off offset:160
	global_load_dwordx4 v[148:151], v[78:79], off offset:160
	global_load_dwordx4 v[152:155], v[40:41], off offset:128
	global_load_dwordx4 v[156:159], v[76:77], off offset:192
	global_load_dwordx4 v[160:163], v[78:79], off offset:192
	global_load_dwordx4 v[164:167], v[40:41], off offset:160
	global_load_dwordx4 v[168:171], v[76:77], off offset:224
	global_load_dwordx4 v[172:175], v[78:79], off offset:224
	s_waitcnt vmcnt(22)
	v_mfma_f32_32x32x16_bf16 v[0:15], v[84:87], v[80:83], v[0:15]
	s_waitcnt vmcnt(21)
	v_mfma_f32_32x32x16_bf16 v[16:31], v[88:91], v[80:83], v[16:31]
	s_waitcnt vmcnt(19)
	v_mfma_f32_32x32x16_bf16 v[0:15], v[96:99], v[92:95], v[0:15]
	s_waitcnt vmcnt(18)
	v_mfma_f32_32x32x16_bf16 v[16:31], v[100:103], v[92:95], v[16:31]
	s_waitcnt vmcnt(16)
	v_mfma_f32_32x32x16_bf16 v[0:15], v[108:111], v[104:107], v[0:15]
	s_waitcnt vmcnt(15)
	v_mfma_f32_32x32x16_bf16 v[16:31], v[112:115], v[104:107], v[16:31]
	s_waitcnt vmcnt(13)
	v_mfma_f32_32x32x16_bf16 v[0:15], v[120:123], v[116:119], v[0:15]
	s_waitcnt vmcnt(12)
	v_mfma_f32_32x32x16_bf16 v[16:31], v[124:127], v[116:119], v[16:31]
	s_waitcnt vmcnt(10)
	v_mfma_f32_32x32x16_bf16 v[0:15], v[132:135], v[128:131], v[0:15]
	s_waitcnt vmcnt(9)
	v_mfma_f32_32x32x16_bf16 v[16:31], v[136:139], v[128:131], v[16:31]
	s_waitcnt vmcnt(7)
	v_mfma_f32_32x32x16_bf16 v[0:15], v[144:147], v[140:143], v[0:15]
	s_waitcnt vmcnt(6)
	v_mfma_f32_32x32x16_bf16 v[16:31], v[148:151], v[140:143], v[16:31]
	s_waitcnt vmcnt(4)
	v_mfma_f32_32x32x16_bf16 v[0:15], v[156:159], v[152:155], v[0:15]
	s_waitcnt vmcnt(3)
	v_mfma_f32_32x32x16_bf16 v[16:31], v[160:163], v[152:155], v[16:31]
	s_waitcnt vmcnt(1)
	v_mfma_f32_32x32x16_bf16 v[0:15], v[168:171], v[164:167], v[0:15]
	s_waitcnt vmcnt(0)
	v_mfma_f32_32x32x16_bf16 v[16:31], v[172:175], v[164:167], v[16:31]
	s_movk_i32 s8, 0x100
	s_barrier
	s_nop 7
	ds_write2st64_b32 v45, v0, v1 offset1:1
	s_nop 0
	ds_write2st64_b32 v45, v16, v17 offset0:128 offset1:129
	ds_write2st64_b32 v45, v2, v3 offset0:2 offset1:3
	ds_write2st64_b32 v45, v18, v19 offset0:130 offset1:131
	ds_write2st64_b32 v45, v4, v5 offset0:4 offset1:5
	ds_write2st64_b32 v45, v20, v21 offset0:132 offset1:133
	ds_write2st64_b32 v45, v6, v7 offset0:6 offset1:7
	ds_write2st64_b32 v45, v22, v23 offset0:134 offset1:135
	ds_write2st64_b32 v45, v8, v9 offset0:8 offset1:9
	ds_write2st64_b32 v45, v24, v25 offset0:136 offset1:137
	ds_write2st64_b32 v45, v10, v11 offset0:10 offset1:11
	ds_write2st64_b32 v45, v26, v27 offset0:138 offset1:139
	ds_write2st64_b32 v45, v12, v13 offset0:12 offset1:13
	ds_write2st64_b32 v45, v28, v29 offset0:140 offset1:141
	ds_write2st64_b32 v45, v14, v15 offset0:14 offset1:15
	ds_write2st64_b32 v45, v30, v31 offset0:142 offset1:143
	s_waitcnt lgkmcnt(0)
	s_barrier
	ds_read2st64_b32 v[0:1], v44 offset1:1
	ds_read2st64_b32 v[2:3], v44 offset0:16 offset1:17
	ds_read2st64_b32 v[4:5], v44 offset0:32 offset1:33
	ds_read2st64_b32 v[6:7], v44 offset0:48 offset1:49
	ds_read2st64_b32 v[8:9], v44 offset0:128 offset1:129
	ds_read2st64_b32 v[10:11], v44 offset0:144 offset1:145
	ds_read2st64_b32 v[12:13], v44 offset0:160 offset1:161
	ds_read2st64_b32 v[14:15], v44 offset0:176 offset1:177
	ds_read2st64_b32 v[16:17], v44 offset0:64 offset1:65
	ds_read2st64_b32 v[18:19], v44 offset0:80 offset1:81
	ds_read2st64_b32 v[20:21], v44 offset0:96 offset1:97
	ds_read2st64_b32 v[22:23], v44 offset0:112 offset1:113
	ds_read2st64_b32 v[24:25], v44 offset0:192 offset1:193
	ds_read2st64_b32 v[26:27], v44 offset0:208 offset1:209
	ds_read2st64_b32 v[28:29], v44 offset0:224 offset1:225
	ds_read2st64_b32 v[30:31], v44 offset0:240 offset1:241
	s_waitcnt lgkmcnt(11)
	v_mov_b32_e32 v38, v8
	v_mov_b32_e32 v39, v0
	v_pk_add_f32 v[38:39], v[38:39], 0 op_sel_hi:[1,0]
	s_waitcnt lgkmcnt(10)
	v_mov_b32_e32 v40, v10
	v_mov_b32_e32 v41, v2
	v_mov_b32_e32 v0, v9
	v_pk_add_f32 v[38:39], v[38:39], v[40:41]
	s_waitcnt lgkmcnt(9)
	v_mov_b32_e32 v40, v12
	v_mov_b32_e32 v41, v4
	v_pk_add_f32 v[0:1], v[0:1], 0 op_sel_hi:[1,0]
	v_mov_b32_e32 v2, v11
	v_pk_add_f32 v[38:39], v[38:39], v[40:41]
	s_waitcnt lgkmcnt(8)
	v_mov_b32_e32 v40, v14
	v_mov_b32_e32 v41, v6
	v_pk_add_f32 v[0:1], v[0:1], v[2:3]
	v_mov_b32_e32 v4, v13
	v_pk_add_f32 v[38:39], v[38:39], v[40:41]
	s_waitcnt lgkmcnt(3)
	v_mov_b32_e32 v40, v24
	v_mov_b32_e32 v41, v16
	v_pk_add_f32 v[0:1], v[0:1], v[4:5]
	v_mov_b32_e32 v6, v15
	v_pk_add_f32 v[38:39], v[38:39], v[40:41]
	s_waitcnt lgkmcnt(2)
	v_mov_b32_e32 v40, v26
	v_mov_b32_e32 v41, v18
	v_pk_add_f32 v[0:1], v[0:1], v[6:7]
	v_mov_b32_e32 v16, v25
	v_pk_add_f32 v[38:39], v[38:39], v[40:41]
	s_waitcnt lgkmcnt(1)
	v_mov_b32_e32 v40, v28
	v_mov_b32_e32 v41, v20
	v_pk_add_f32 v[0:1], v[0:1], v[16:17]
	v_mov_b32_e32 v18, v27
	v_pk_add_f32 v[38:39], v[38:39], v[40:41]
	s_waitcnt lgkmcnt(0)
	v_mov_b32_e32 v40, v30
	v_mov_b32_e32 v41, v22
	v_pk_add_f32 v[0:1], v[0:1], v[18:19]
	v_mov_b32_e32 v20, v29
	v_pk_add_f32 v[38:39], v[38:39], v[40:41]
	v_pk_add_f32 v[0:1], v[0:1], v[20:21]
	v_mov_b32_e32 v22, v31
	v_pk_add_f32 v[0:1], v[0:1], v[22:23]
	v_mul_f32_e32 v2, 0xbfb8aa3b, v39
	v_exp_f32_e32 v2, v2
	v_mul_f32_e32 v3, 0xbfb8aa3b, v1
	v_exp_f32_e32 v3, v3
	s_lshl_b32 s0, s17, 3
	v_add_f32_e32 v2, 1.0, v2
	v_rcp_f32_e32 v4, v2
	v_add_f32_e32 v2, 1.0, v3
	v_rcp_f32_e32 v3, v2
	s_andn2_b32 s0, s0, 31
	v_mul_f32_e32 v4, v39, v4
	v_mul_f32_e32 v4, v38, v4
	v_mul_f32_e32 v1, v1, v3
	v_mul_f32_e32 v0, v0, v1
	v_add_u32_e32 v2, s0, v43
	v_cvt_pk_bf16_f32 v4, v4, v0
	v_mov_b64_e32 v[0:1], s[4:5]
	s_add_i32 s10, s10, 1
	s_add_i32 s11, s11, s70
	s_add_i32 s16, s16, s46
	s_add_i32 s12, s12, s71
	v_mad_u64_u32 v[0:1], s[0:1], v36, s15, v[0:1]
	v_ashrrev_i32_e32 v3, 31, v2
	s_cmp_eq_u32 s10, s44
	v_lshl_add_u64 v[0:1], v[2:3], 1, v[0:1]
	s_cselect_b64 s[8:9], -1, 0
	global_store_dword v[0:1], v4, off
	s_branch .LBB0_198

; template <int MODE>
; __device__ __forceinline__ void small_gemm(LAS unsigned char* lds, const bf16* A, const bf16* Bt, int N, int K, bf16* O, int ldc, int act_cols, const float* bias, const bf16* Yv, int ldy, int it0, int it1) {
;     ...
;     for (int it = it0; it < it1; ++it) {
;         const int item = BX + it * GSZ; if (item >= nitems) break;
;         const int rt = item & 3, ct = item >> 2;
;         const int hc = 32 * ct + tl;
;         const int brow = (MODE == 3) ? (256 * (hc >> 7) + (hc & 127)) : hc;
;         const bf16* ap = A + (size_t)(32 * rt + tl) * K + wave * kw + 8 * hh;
;         const bf16* bp = Bt + (size_t)brow * K + wave * kw + 8 * hh;
;         v16f acc0, acc1;
; #pragma unroll
;         for (int r = 0; r < 16; ++r) { acc0[r] = 0.f; acc1[r] = 0.f; }
; #pragma unroll 4
;         for (int ks = 0; ks < nks; ++ks) {
;             const bfx8 a = *(const bfx8*)(ap + 16 * ks);
;             const bfx8 b0 = *(const bfx8*)(bp + 16 * ks);
;             acc0 = __builtin_amdgcn_mfma_f32_32x32x16_bf16(b0, a, acc0, 0, 0, 0);
;             if (MODE == 3) { const bfx8 b1 = *(const bfx8*)(bp + (size_t)128 * K + 16 * ks); acc1 = __builtin_amdgcn_mfma_f32_32x32x16_bf16(b1, a, acc1, 0, 0, 0); }
;         }
;         __syncthreads();
; #pragma unroll
;         for (int r = 0; r < 16; ++r) { red[(wave * 16 + r) * 64 + lane] = acc0[r]; if (MODE == 3) red[8192 + (wave * 16 + r) * 64 + lane] = acc1[r]; }
;         __syncthreads();
;         float v0[2], v1[2];
; #pragma unroll
;         for (int e = 0; e < 2; ++e) { float s0 = 0.f, s1 = 0.f;
; #pragma unroll
;             for (int w = 0; w < 8; ++w) { s0 += red[(w * 16 + 2 * wave + e) * 64 + lane]; if (MODE == 3) s1 += red[8192 + (w * 16 + 2 * wave + e) * 64 + lane]; }
;             v0[e] = s0; v1[e] = s1; }
;         const int reg = 2 * wave;
;         const int col = 32 * ct + (reg & 3) + 8 * (reg >> 2) + 4 * hh;
;         const size_t row = (size_t)(32 * rt + tl);
;         float o0 = v0[0], o1 = v0[1];
;         if (MODE == 1) { if (col < act_cols) { o0 = gelu_t(o0); o1 = gelu_t(o1); } }
;         if (MODE == 2) { const unsigned y = *(const unsigned*)(Yv + row * ldy + col); o0 = bf_lo(y) * pg8::sigmoid_f(o0 + bias[col]); o1 = bf_hi(y) * pg8::sigmoid_f(o1 + bias[col + 1]); }
;         if (MODE == 3) { o0 = pg8::silu_f(o0) * v1[0]; o1 = pg8::silu_f(o1) * v1[1]; }
.LBB0_223:
	v_add_co_u32_e32 v76, vcc, s10, v38
	s_nop 1
	v_addc_co_u32_e32 v77, vcc, 0, v39, vcc
	v_add_co_u32_e32 v78, vcc, s11, v38
	s_nop 1
	v_addc_co_u32_e32 v79, vcc, 0, v39, vcc
	global_load_dwordx4 v[80:83], v[40:41], off offset:-64
	global_load_dwordx4 v[84:87], v[76:77], off
	global_load_dwordx4 v[88:91], v[78:79], off
	global_load_dwordx4 v[92:95], v[40:41], off offset:-32
	global_load_dwordx4 v[96:99], v[76:77], off offset:32
	global_load_dwordx4 v[100:103], v[78:79], off offset:32
	global_load_dwordx4 v[104:107], v[40:41], off
	global_load_dwordx4 v[108:111], v[76:77], off offset:64
	global_load_dwordx4 v[112:115], v[78:79], off offset:64
	global_load_dwordx4 v[116:119], v[40:41], off offset:32
	global_load_dwordx4 v[120:123], v[76:77], off offset:96
	global_load_dwordx4 v[124:127], v[78:79], off offset:96
	global_load_dwordx4 v[128:131], v[40:41], off offset:64
	global_load_dwordx4 v[132:135], v[76:77], off offset:128
	global_load_dwordx4 v[136:139], v[78:79], off offset:128
	global_load_dwordx4 v[140:143], v[40:41], off offset:96
	global_load_dwordx4 v[144:147], v[76:77], off offset:160
	global_load_dwordx4 v[148:151], v[78:79], off offset:160
	global_load_dwordx4 v[152:155], v[40:41], off offset:128
	global_load_dwordx4 v[156:159], v[76:77], off offset:192
	global_load_dwordx4 v[160:163], v[78:79], off offset:192
	global_load_dwordx4 v[164:167], v[40:41], off offset:160
	global_load_dwordx4 v[168:171], v[76:77], off offset:224
	global_load_dwordx4 v[172:175], v[78:79], off offset:224
	s_waitcnt vmcnt(22)
	v_mfma_f32_32x32x16_bf16 v[0:15], v[84:87], v[80:83], v[0:15]
	s_waitcnt vmcnt(21)
	v_mfma_f32_32x32x16_bf16 v[16:31], v[88:91], v[80:83], v[16:31]
	s_waitcnt vmcnt(19)
	v_mfma_f32_32x32x16_bf16 v[0:15], v[96:99], v[92:95], v[0:15]
	s_waitcnt vmcnt(18)
	v_mfma_f32_32x32x16_bf16 v[16:31], v[100:103], v[92:95], v[16:31]
	s_waitcnt vmcnt(16)
	v_mfma_f32_32x32x16_bf16 v[0:15], v[108:111], v[104:107], v[0:15]
	s_waitcnt vmcnt(15)
	v_mfma_f32_32x32x16_bf16 v[16:31], v[112:115], v[104:107], v[16:31]
	s_waitcnt vmcnt(13)
	v_mfma_f32_32x32x16_bf16 v[0:15], v[120:123], v[116:119], v[0:15]
	s_waitcnt vmcnt(12)
	v_mfma_f32_32x32x16_bf16 v[16:31], v[124:127], v[116:119], v[16:31]
	s_waitcnt vmcnt(10)
	v_mfma_f32_32x32x16_bf16 v[0:15], v[132:135], v[128:131], v[0:15]
	s_waitcnt vmcnt(9)
	v_mfma_f32_32x32x16_bf16 v[16:31], v[136:139], v[128:131], v[16:31]
	s_waitcnt vmcnt(7)
	v_mfma_f32_32x32x16_bf16 v[0:15], v[144:147], v[140:143], v[0:15]
	s_waitcnt vmcnt(6)
	v_mfma_f32_32x32x16_bf16 v[16:31], v[148:151], v[140:143], v[16:31]
	s_waitcnt vmcnt(4)
	v_mfma_f32_32x32x16_bf16 v[0:15], v[156:159], v[152:155], v[0:15]
	s_waitcnt vmcnt(3)
	v_mfma_f32_32x32x16_bf16 v[16:31], v[160:163], v[152:155], v[16:31]
	s_waitcnt vmcnt(1)
	v_mfma_f32_32x32x16_bf16 v[0:15], v[168:171], v[164:167], v[0:15]
	s_waitcnt vmcnt(0)
	v_mfma_f32_32x32x16_bf16 v[16:31], v[172:175], v[164:167], v[16:31]
	s_movk_i32 s8, 0x100
	s_barrier
	s_nop 7
	ds_write2st64_b32 v45, v0, v1 offset1:1
	s_nop 0
	ds_write2st64_b32 v45, v16, v17 offset0:128 offset1:129
	ds_write2st64_b32 v45, v2, v3 offset0:2 offset1:3
	ds_write2st64_b32 v45, v18, v19 offset0:130 offset1:131
	ds_write2st64_b32 v45, v4, v5 offset0:4 offset1:5
	ds_write2st64_b32 v45, v20, v21 offset0:132 offset1:133
	ds_write2st64_b32 v45, v6, v7 offset0:6 offset1:7
	ds_write2st64_b32 v45, v22, v23 offset0:134 offset1:135
	ds_write2st64_b32 v45, v8, v9 offset0:8 offset1:9
	ds_write2st64_b32 v45, v24, v25 offset0:136 offset1:137
	ds_write2st64_b32 v45, v10, v11 offset0:10 offset1:11
	ds_write2st64_b32 v45, v26, v27 offset0:138 offset1:139
	ds_write2st64_b32 v45, v12, v13 offset0:12 offset1:13
	ds_write2st64_b32 v45, v28, v29 offset0:140 offset1:141
	ds_write2st64_b32 v45, v14, v15 offset0:14 offset1:15
	ds_write2st64_b32 v45, v30, v31 offset0:142 offset1:143
	s_waitcnt lgkmcnt(0)
	s_barrier
	ds_read2st64_b32 v[0:1], v44 offset1:1
	ds_read2st64_b32 v[2:3], v44 offset0:16 offset1:17
	ds_read2st64_b32 v[4:5], v44 offset0:32 offset1:33
	ds_read2st64_b32 v[6:7], v44 offset0:48 offset1:49
	ds_read2st64_b32 v[8:9], v44 offset0:128 offset1:129
	ds_read2st64_b32 v[10:11], v44 offset0:144 offset1:145
	ds_read2st64_b32 v[12:13], v44 offset0:160 offset1:161
	ds_read2st64_b32 v[14:15], v44 offset0:176 offset1:177
	ds_read2st64_b32 v[16:17], v44 offset0:64 offset1:65
	ds_read2st64_b32 v[18:19], v44 offset0:80 offset1:81
	ds_read2st64_b32 v[20:21], v44 offset0:96 offset1:97
	ds_read2st64_b32 v[22:23], v44 offset0:112 offset1:113
	ds_read2st64_b32 v[24:25], v44 offset0:192 offset1:193
	ds_read2st64_b32 v[26:27], v44 offset0:208 offset1:209
	ds_read2st64_b32 v[28:29], v44 offset0:224 offset1:225
	ds_read2st64_b32 v[30:31], v44 offset0:240 offset1:241
	s_waitcnt lgkmcnt(11)
	v_mov_b32_e32 v38, v8
	v_mov_b32_e32 v39, v0
	v_pk_add_f32 v[38:39], v[38:39], 0 op_sel_hi:[1,0]
	s_waitcnt lgkmcnt(10)
	v_mov_b32_e32 v40, v10
	v_mov_b32_e32 v41, v2
	v_mov_b32_e32 v0, v9
	v_pk_add_f32 v[38:39], v[38:39], v[40:41]
	s_waitcnt lgkmcnt(9)
	v_mov_b32_e32 v40, v12
	v_mov_b32_e32 v41, v4
	v_pk_add_f32 v[0:1], v[0:1], 0 op_sel_hi:[1,0]
	v_mov_b32_e32 v2, v11
	v_pk_add_f32 v[38:39], v[38:39], v[40:41]
	s_waitcnt lgkmcnt(8)
	v_mov_b32_e32 v40, v14
	v_mov_b32_e32 v41, v6
	v_pk_add_f32 v[0:1], v[0:1], v[2:3]
	v_mov_b32_e32 v4, v13
	v_pk_add_f32 v[38:39], v[38:39], v[40:41]
	s_waitcnt lgkmcnt(3)
	v_mov_b32_e32 v40, v24
	v_mov_b32_e32 v41, v16
	v_pk_add_f32 v[0:1], v[0:1], v[4:5]
	v_mov_b32_e32 v6, v15
	v_pk_add_f32 v[38:39], v[38:39], v[40:41]
	s_waitcnt lgkmcnt(2)
	v_mov_b32_e32 v40, v26
	v_mov_b32_e32 v41, v18
	v_pk_add_f32 v[0:1], v[0:1], v[6:7]
	v_mov_b32_e32 v16, v25
	v_pk_add_f32 v[38:39], v[38:39], v[40:41]
	s_waitcnt lgkmcnt(1)
	v_mov_b32_e32 v40, v28
	v_mov_b32_e32 v41, v20
	v_pk_add_f32 v[0:1], v[0:1], v[16:17]
	v_mov_b32_e32 v18, v27
	v_pk_add_f32 v[38:39], v[38:39], v[40:41]
	s_waitcnt lgkmcnt(0)
	v_mov_b32_e32 v40, v30
	v_mov_b32_e32 v41, v22
	v_pk_add_f32 v[0:1], v[0:1], v[18:19]
	v_mov_b32_e32 v20, v29
	v_pk_add_f32 v[38:39], v[38:39], v[40:41]
	v_pk_add_f32 v[0:1], v[0:1], v[20:21]
	v_mov_b32_e32 v22, v31
	v_pk_add_f32 v[0:1], v[0:1], v[22:23]
	v_mul_f32_e32 v2, 0xbfb8aa3b, v39
	v_exp_f32_e32 v2, v2
	v_mul_f32_e32 v3, 0xbfb8aa3b, v1
	v_exp_f32_e32 v3, v3
	s_lshl_b32 s0, s17, 3
	v_add_f32_e32 v2, 1.0, v2
	v_rcp_f32_e32 v4, v2
	v_add_f32_e32 v2, 1.0, v3
	v_rcp_f32_e32 v3, v2
	s_andn2_b32 s0, s0, 31
	v_mul_f32_e32 v4, v39, v4
	v_mul_f32_e32 v4, v38, v4
	v_mul_f32_e32 v1, v1, v3
	v_mul_f32_e32 v0, v0, v1
	v_cvt_pk_bf16_f32 v4, v4, v0
	v_mov_b64_e32 v[0:1], s[4:5]
	v_add_u32_e32 v2, s0, v43
	v_mad_u64_u32 v[0:1], s[0:1], v36, s12, v[0:1]
	s_add_i32 s0, s16, 1
	s_add_i32 s15, s15, s70
	s_add_i32 s14, s14, s46
	s_add_i32 s13, s13, s71
	v_ashrrev_i32_e32 v3, 31, v2
	s_cmp_gt_u32 s16, 2
	v_lshl_add_u64 v[0:1], v[2:3], 1, v[0:1]
	s_cselect_b64 s[8:9], -1, 0
	s_mov_b32 s16, s0
	global_store_dword v[0:1], v4, off
	s_branch .LBB0_220

; template <int MODE>
; __device__ __forceinline__ void small_gemm(LAS unsigned char* lds, const bf16* A, const bf16* Bt, int N, int K, bf16* O, int ldc, int act_cols, const float* bias, const bf16* Yv, int ldy, int it0, int it1) {
;     ...
;     for (int it = it0; it < it1; ++it) {
;         const int item = BX + it * GSZ; if (item >= nitems) break;
;         const int rt = item & 3, ct = item >> 2;
;         const int hc = 32 * ct + tl;
;         const int brow = (MODE == 3) ? (256 * (hc >> 7) + (hc & 127)) : hc;
;         const bf16* ap = A + (size_t)(32 * rt + tl) * K + wave * kw + 8 * hh;
;         const bf16* bp = Bt + (size_t)brow * K + wave * kw + 8 * hh;
;         v16f acc0, acc1;
; #pragma unroll
;         for (int r = 0; r < 16; ++r) { acc0[r] = 0.f; acc1[r] = 0.f; }
; #pragma unroll 4
;         for (int ks = 0; ks < nks; ++ks) {
;             const bfx8 a = *(const bfx8*)(ap + 16 * ks);
;             const bfx8 b0 = *(const bfx8*)(bp + 16 * ks);
;             acc0 = __builtin_amdgcn_mfma_f32_32x32x16_bf16(b0, a, acc0, 0, 0, 0);
;             if (MODE == 3) { const bfx8 b1 = *(const bfx8*)(bp + (size_t)128 * K + 16 * ks); acc1 = __builtin_amdgcn_mfma_f32_32x32x16_bf16(b1, a, acc1, 0, 0, 0); }
;         }
;         __syncthreads();
; #pragma unroll
;         for (int r = 0; r < 16; ++r) { red[(wave * 16 + r) * 64 + lane] = acc0[r]; if (MODE == 3) red[8192 + (wave * 16 + r) * 64 + lane] = acc1[r]; }
;         __syncthreads();
;         float v0[2], v1[2];
; #pragma unroll
;         for (int e = 0; e < 2; ++e) { float s0 = 0.f, s1 = 0.f;
; #pragma unroll
;             for (int w = 0; w < 8; ++w) { s0 += red[(w * 16 + 2 * wave + e) * 64 + lane]; if (MODE == 3) s1 += red[8192 + (w * 16 + 2 * wave + e) * 64 + lane]; }
;             v0[e] = s0; v1[e] = s1; }
;         const int reg = 2 * wave;
;         const int col = 32 * ct + (reg & 3) + 8 * (reg >> 2) + 4 * hh;
;         const size_t row = (size_t)(32 * rt + tl);
;         float o0 = v0[0], o1 = v0[1];
;         if (MODE == 1) { if (col < act_cols) { o0 = gelu_t(o0); o1 = gelu_t(o1); } }
;         if (MODE == 2) { const unsigned y = *(const unsigned*)(Yv + row * ldy + col); o0 = bf_lo(y) * pg8::sigmoid_f(o0 + bias[col]); o1 = bf_hi(y) * pg8::sigmoid_f(o1 + bias[col + 1]); }
;         if (MODE == 3) { o0 = pg8::silu_f(o0) * v1[0]; o1 = pg8::silu_f(o1) * v1[1]; }
.LBB0_1107:
	v_add_co_u32_e32 v76, vcc, s17, v38
	s_nop 1
	v_addc_co_u32_e32 v77, vcc, 0, v39, vcc
	v_add_co_u32_e32 v78, vcc, s18, v38
	s_nop 1
	v_addc_co_u32_e32 v79, vcc, 0, v39, vcc
	global_load_dwordx4 v[80:83], v[40:41], off offset:-64
	global_load_dwordx4 v[84:87], v[76:77], off
	global_load_dwordx4 v[88:91], v[78:79], off
	global_load_dwordx4 v[92:95], v[40:41], off offset:-32
	global_load_dwordx4 v[96:99], v[76:77], off offset:32
	global_load_dwordx4 v[100:103], v[78:79], off offset:32
	global_load_dwordx4 v[104:107], v[40:41], off
	global_load_dwordx4 v[108:111], v[76:77], off offset:64
	global_load_dwordx4 v[112:115], v[78:79], off offset:64
	global_load_dwordx4 v[116:119], v[40:41], off offset:32
	global_load_dwordx4 v[120:123], v[76:77], off offset:96
	global_load_dwordx4 v[124:127], v[78:79], off offset:96
	global_load_dwordx4 v[128:131], v[40:41], off offset:64
	global_load_dwordx4 v[132:135], v[76:77], off offset:128
	global_load_dwordx4 v[136:139], v[78:79], off offset:128
	global_load_dwordx4 v[140:143], v[40:41], off offset:96
	global_load_dwordx4 v[144:147], v[76:77], off offset:160
	global_load_dwordx4 v[148:151], v[78:79], off offset:160
	global_load_dwordx4 v[152:155], v[40:41], off offset:128
	global_load_dwordx4 v[156:159], v[76:77], off offset:192
	global_load_dwordx4 v[160:163], v[78:79], off offset:192
	global_load_dwordx4 v[164:167], v[40:41], off offset:160
	global_load_dwordx4 v[168:171], v[76:77], off offset:224
	global_load_dwordx4 v[172:175], v[78:79], off offset:224
	s_waitcnt vmcnt(22)
	v_mfma_f32_32x32x16_bf16 v[0:15], v[84:87], v[80:83], v[0:15]
	s_waitcnt vmcnt(21)
	v_mfma_f32_32x32x16_bf16 v[16:31], v[88:91], v[80:83], v[16:31]
	s_waitcnt vmcnt(19)
	v_mfma_f32_32x32x16_bf16 v[0:15], v[96:99], v[92:95], v[0:15]
	s_waitcnt vmcnt(18)
	v_mfma_f32_32x32x16_bf16 v[16:31], v[100:103], v[92:95], v[16:31]
	s_waitcnt vmcnt(16)
	v_mfma_f32_32x32x16_bf16 v[0:15], v[108:111], v[104:107], v[0:15]
	s_waitcnt vmcnt(15)
	v_mfma_f32_32x32x16_bf16 v[16:31], v[112:115], v[104:107], v[16:31]
	s_waitcnt vmcnt(13)
	v_mfma_f32_32x32x16_bf16 v[0:15], v[120:123], v[116:119], v[0:15]
	s_waitcnt vmcnt(12)
	v_mfma_f32_32x32x16_bf16 v[16:31], v[124:127], v[116:119], v[16:31]
	s_waitcnt vmcnt(10)
	v_mfma_f32_32x32x16_bf16 v[0:15], v[132:135], v[128:131], v[0:15]
	s_waitcnt vmcnt(9)
	v_mfma_f32_32x32x16_bf16 v[16:31], v[136:139], v[128:131], v[16:31]
	s_waitcnt vmcnt(7)
	v_mfma_f32_32x32x16_bf16 v[0:15], v[144:147], v[140:143], v[0:15]
	s_waitcnt vmcnt(6)
	v_mfma_f32_32x32x16_bf16 v[16:31], v[148:151], v[140:143], v[16:31]
	s_waitcnt vmcnt(4)
	v_mfma_f32_32x32x16_bf16 v[0:15], v[156:159], v[152:155], v[0:15]
	s_waitcnt vmcnt(3)
	v_mfma_f32_32x32x16_bf16 v[16:31], v[160:163], v[152:155], v[16:31]
	s_waitcnt vmcnt(1)
	v_mfma_f32_32x32x16_bf16 v[0:15], v[168:171], v[164:167], v[0:15]
	s_waitcnt vmcnt(0)
	v_mfma_f32_32x32x16_bf16 v[16:31], v[172:175], v[164:167], v[16:31]
	s_movk_i32 s12, 0x100
	s_barrier
	s_nop 7
	ds_write2st64_b32 v45, v0, v1 offset1:1
	s_nop 0
	ds_write2st64_b32 v45, v16, v17 offset0:128 offset1:129
	ds_write2st64_b32 v45, v2, v3 offset0:2 offset1:3
	ds_write2st64_b32 v45, v18, v19 offset0:130 offset1:131
	ds_write2st64_b32 v45, v4, v5 offset0:4 offset1:5
	ds_write2st64_b32 v45, v20, v21 offset0:132 offset1:133
	ds_write2st64_b32 v45, v6, v7 offset0:6 offset1:7
	ds_write2st64_b32 v45, v22, v23 offset0:134 offset1:135
	ds_write2st64_b32 v45, v8, v9 offset0:8 offset1:9
	ds_write2st64_b32 v45, v24, v25 offset0:136 offset1:137
	ds_write2st64_b32 v45, v10, v11 offset0:10 offset1:11
	ds_write2st64_b32 v45, v26, v27 offset0:138 offset1:139
	ds_write2st64_b32 v45, v12, v13 offset0:12 offset1:13
	ds_write2st64_b32 v45, v28, v29 offset0:140 offset1:141
	ds_write2st64_b32 v45, v14, v15 offset0:14 offset1:15
	ds_write2st64_b32 v45, v30, v31 offset0:142 offset1:143
	s_waitcnt lgkmcnt(0)
	s_barrier
	ds_read2st64_b32 v[0:1], v44 offset1:1
	ds_read2st64_b32 v[2:3], v44 offset0:16 offset1:17
	ds_read2st64_b32 v[4:5], v44 offset0:32 offset1:33
	ds_read2st64_b32 v[6:7], v44 offset0:48 offset1:49
	ds_read2st64_b32 v[8:9], v44 offset0:128 offset1:129
	ds_read2st64_b32 v[10:11], v44 offset0:144 offset1:145
	ds_read2st64_b32 v[12:13], v44 offset0:160 offset1:161
	ds_read2st64_b32 v[14:15], v44 offset0:176 offset1:177
	ds_read2st64_b32 v[16:17], v44 offset0:64 offset1:65
	ds_read2st64_b32 v[18:19], v44 offset0:80 offset1:81
	ds_read2st64_b32 v[20:21], v44 offset0:96 offset1:97
	ds_read2st64_b32 v[22:23], v44 offset0:112 offset1:113
	ds_read2st64_b32 v[24:25], v44 offset0:192 offset1:193
	ds_read2st64_b32 v[26:27], v44 offset0:208 offset1:209
	ds_read2st64_b32 v[28:29], v44 offset0:224 offset1:225
	ds_read2st64_b32 v[30:31], v44 offset0:240 offset1:241
	s_waitcnt lgkmcnt(11)
	v_mov_b32_e32 v38, v8
	v_mov_b32_e32 v39, v0
	v_pk_add_f32 v[38:39], v[38:39], 0 op_sel_hi:[1,0]
	s_waitcnt lgkmcnt(10)
	v_mov_b32_e32 v40, v10
	v_mov_b32_e32 v41, v2
	v_mov_b32_e32 v0, v9
	v_pk_add_f32 v[38:39], v[38:39], v[40:41]
	s_waitcnt lgkmcnt(9)
	v_mov_b32_e32 v40, v12
	v_mov_b32_e32 v41, v4
	v_pk_add_f32 v[0:1], v[0:1], 0 op_sel_hi:[1,0]
	v_mov_b32_e32 v2, v11
	v_pk_add_f32 v[38:39], v[38:39], v[40:41]
	s_waitcnt lgkmcnt(8)
	v_mov_b32_e32 v40, v14
	v_mov_b32_e32 v41, v6
	v_pk_add_f32 v[0:1], v[0:1], v[2:3]
	v_mov_b32_e32 v4, v13
	v_pk_add_f32 v[38:39], v[38:39], v[40:41]
	s_waitcnt lgkmcnt(3)
	v_mov_b32_e32 v40, v24
	v_mov_b32_e32 v41, v16
	v_pk_add_f32 v[0:1], v[0:1], v[4:5]
	v_mov_b32_e32 v6, v15
	v_pk_add_f32 v[38:39], v[38:39], v[40:41]
	s_waitcnt lgkmcnt(2)
	v_mov_b32_e32 v40, v26
	v_mov_b32_e32 v41, v18
	v_pk_add_f32 v[0:1], v[0:1], v[6:7]
	v_mov_b32_e32 v16, v25
	v_pk_add_f32 v[38:39], v[38:39], v[40:41]
	s_waitcnt lgkmcnt(1)
	v_mov_b32_e32 v40, v28
	v_mov_b32_e32 v41, v20
	v_pk_add_f32 v[0:1], v[0:1], v[16:17]
	v_mov_b32_e32 v18, v27
	v_pk_add_f32 v[38:39], v[38:39], v[40:41]
	s_waitcnt lgkmcnt(0)
	v_mov_b32_e32 v40, v30
	v_mov_b32_e32 v41, v22
	v_pk_add_f32 v[0:1], v[0:1], v[18:19]
	v_mov_b32_e32 v20, v29
	v_pk_add_f32 v[38:39], v[38:39], v[40:41]
	v_pk_add_f32 v[0:1], v[0:1], v[20:21]
	v_mov_b32_e32 v22, v31
	v_pk_add_f32 v[0:1], v[0:1], v[22:23]
	v_mul_f32_e32 v2, 0xbfb8aa3b, v39
	v_exp_f32_e32 v2, v2
	v_mul_f32_e32 v3, 0xbfb8aa3b, v1
	v_exp_f32_e32 v3, v3
	s_lshl_b32 s0, s21, 3
	v_add_f32_e32 v2, 1.0, v2
	v_rcp_f32_e32 v4, v2
	v_add_f32_e32 v2, 1.0, v3
	v_rcp_f32_e32 v3, v2
	s_andn2_b32 s0, s0, 31
	v_mul_f32_e32 v4, v39, v4
	v_mul_f32_e32 v4, v38, v4
	v_mul_f32_e32 v1, v1, v3
	v_mul_f32_e32 v0, v0, v1
	v_add_u32_e32 v2, s0, v43
	v_cvt_pk_bf16_f32 v4, v4, v0
	v_mov_b64_e32 v[0:1], s[10:11]
	s_add_i32 s14, s14, 1
	s_add_i32 s15, s15, s70
	s_add_i32 s20, s20, s46
	s_add_i32 s16, s16, s71
	v_mad_u64_u32 v[0:1], s[0:1], v36, s19, v[0:1]
	v_ashrrev_i32_e32 v3, 31, v2
	s_cmp_eq_u32 s14, s44
	v_lshl_add_u64 v[0:1], v[2:3], 1, v[0:1]
	s_cselect_b64 s[12:13], -1, 0
	global_store_dword v[0:1], v4, off
	s_branch .LBB0_1104

; template <int MODE>
; __device__ __forceinline__ void small_gemm(LAS unsigned char* lds, const bf16* A, const bf16* Bt, int N, int K, bf16* O, int ldc, int act_cols, const float* bias, const bf16* Yv, int ldy, int it0, int it1) {
;     ...
;     for (int it = it0; it < it1; ++it) {
;         const int item = BX + it * GSZ; if (item >= nitems) break;
;         const int rt = item & 3, ct = item >> 2;
;         const int hc = 32 * ct + tl;
;         const int brow = (MODE == 3) ? (256 * (hc >> 7) + (hc & 127)) : hc;
;         const bf16* ap = A + (size_t)(32 * rt + tl) * K + wave * kw + 8 * hh;
;         const bf16* bp = Bt + (size_t)brow * K + wave * kw + 8 * hh;
;         v16f acc0, acc1;
; #pragma unroll
;         for (int r = 0; r < 16; ++r) { acc0[r] = 0.f; acc1[r] = 0.f; }
; #pragma unroll 4
;         for (int ks = 0; ks < nks; ++ks) {
;             const bfx8 a = *(const bfx8*)(ap + 16 * ks);
;             const bfx8 b0 = *(const bfx8*)(bp + 16 * ks);
;             acc0 = __builtin_amdgcn_mfma_f32_32x32x16_bf16(b0, a, acc0, 0, 0, 0);
;             if (MODE == 3) { const bfx8 b1 = *(const bfx8*)(bp + (size_t)128 * K + 16 * ks); acc1 = __builtin_amdgcn_mfma_f32_32x32x16_bf16(b1, a, acc1, 0, 0, 0); }
;         }
;         __syncthreads();
; #pragma unroll
;         for (int r = 0; r < 16; ++r) { red[(wave * 16 + r) * 64 + lane] = acc0[r]; if (MODE == 3) red[8192 + (wave * 16 + r) * 64 + lane] = acc1[r]; }
;         __syncthreads();
;         float v0[2], v1[2];
; #pragma unroll
;         for (int e = 0; e < 2; ++e) { float s0 = 0.f, s1 = 0.f;
; #pragma unroll
;             for (int w = 0; w < 8; ++w) { s0 += red[(w * 16 + 2 * wave + e) * 64 + lane]; if (MODE == 3) s1 += red[8192 + (w * 16 + 2 * wave + e) * 64 + lane]; }
;             v0[e] = s0; v1[e] = s1; }
;         const int reg = 2 * wave;
;         const int col = 32 * ct + (reg & 3) + 8 * (reg >> 2) + 4 * hh;
;         const size_t row = (size_t)(32 * rt + tl);
;         float o0 = v0[0], o1 = v0[1];
;         if (MODE == 1) { if (col < act_cols) { o0 = gelu_t(o0); o1 = gelu_t(o1); } }
;         if (MODE == 2) { const unsigned y = *(const unsigned*)(Yv + row * ldy + col); o0 = bf_lo(y) * pg8::sigmoid_f(o0 + bias[col]); o1 = bf_hi(y) * pg8::sigmoid_f(o1 + bias[col + 1]); }
;         if (MODE == 3) { o0 = pg8::silu_f(o0) * v1[0]; o1 = pg8::silu_f(o1) * v1[1]; }
.LBB0_1129:
	v_add_co_u32_e32 v76, vcc, s14, v38
	s_nop 1
	v_addc_co_u32_e32 v77, vcc, 0, v39, vcc
	v_add_co_u32_e32 v78, vcc, s15, v38
	s_nop 1
	v_addc_co_u32_e32 v79, vcc, 0, v39, vcc
	global_load_dwordx4 v[80:83], v[40:41], off offset:-64
	global_load_dwordx4 v[84:87], v[76:77], off
	global_load_dwordx4 v[88:91], v[78:79], off
	global_load_dwordx4 v[92:95], v[40:41], off offset:-32
	global_load_dwordx4 v[96:99], v[76:77], off offset:32
	global_load_dwordx4 v[100:103], v[78:79], off offset:32
	global_load_dwordx4 v[104:107], v[40:41], off
	global_load_dwordx4 v[108:111], v[76:77], off offset:64
	global_load_dwordx4 v[112:115], v[78:79], off offset:64
	global_load_dwordx4 v[116:119], v[40:41], off offset:32
	global_load_dwordx4 v[120:123], v[76:77], off offset:96
	global_load_dwordx4 v[124:127], v[78:79], off offset:96
	global_load_dwordx4 v[128:131], v[40:41], off offset:64
	global_load_dwordx4 v[132:135], v[76:77], off offset:128
	global_load_dwordx4 v[136:139], v[78:79], off offset:128
	global_load_dwordx4 v[140:143], v[40:41], off offset:96
	global_load_dwordx4 v[144:147], v[76:77], off offset:160
	global_load_dwordx4 v[148:151], v[78:79], off offset:160
	global_load_dwordx4 v[152:155], v[40:41], off offset:128
	global_load_dwordx4 v[156:159], v[76:77], off offset:192
	global_load_dwordx4 v[160:163], v[78:79], off offset:192
	global_load_dwordx4 v[164:167], v[40:41], off offset:160
	global_load_dwordx4 v[168:171], v[76:77], off offset:224
	global_load_dwordx4 v[172:175], v[78:79], off offset:224
	s_waitcnt vmcnt(22)
	v_mfma_f32_32x32x16_bf16 v[0:15], v[84:87], v[80:83], v[0:15]
	s_waitcnt vmcnt(21)
	v_mfma_f32_32x32x16_bf16 v[16:31], v[88:91], v[80:83], v[16:31]
	s_waitcnt vmcnt(19)
	v_mfma_f32_32x32x16_bf16 v[0:15], v[96:99], v[92:95], v[0:15]
	s_waitcnt vmcnt(18)
	v_mfma_f32_32x32x16_bf16 v[16:31], v[100:103], v[92:95], v[16:31]
	s_waitcnt vmcnt(16)
	v_mfma_f32_32x32x16_bf16 v[0:15], v[108:111], v[104:107], v[0:15]
	s_waitcnt vmcnt(15)
	v_mfma_f32_32x32x16_bf16 v[16:31], v[112:115], v[104:107], v[16:31]
	s_waitcnt vmcnt(13)
	v_mfma_f32_32x32x16_bf16 v[0:15], v[120:123], v[116:119], v[0:15]
	s_waitcnt vmcnt(12)
	v_mfma_f32_32x32x16_bf16 v[16:31], v[124:127], v[116:119], v[16:31]
	s_waitcnt vmcnt(10)
	v_mfma_f32_32x32x16_bf16 v[0:15], v[132:135], v[128:131], v[0:15]
	s_waitcnt vmcnt(9)
	v_mfma_f32_32x32x16_bf16 v[16:31], v[136:139], v[128:131], v[16:31]
	s_waitcnt vmcnt(7)
	v_mfma_f32_32x32x16_bf16 v[0:15], v[144:147], v[140:143], v[0:15]
	s_waitcnt vmcnt(6)
	v_mfma_f32_32x32x16_bf16 v[16:31], v[148:151], v[140:143], v[16:31]
	s_waitcnt vmcnt(4)
	v_mfma_f32_32x32x16_bf16 v[0:15], v[156:159], v[152:155], v[0:15]
	s_waitcnt vmcnt(3)
	v_mfma_f32_32x32x16_bf16 v[16:31], v[160:163], v[152:155], v[16:31]
	s_waitcnt vmcnt(1)
	v_mfma_f32_32x32x16_bf16 v[0:15], v[168:171], v[164:167], v[0:15]
	s_waitcnt vmcnt(0)
	v_mfma_f32_32x32x16_bf16 v[16:31], v[172:175], v[164:167], v[16:31]
	s_movk_i32 s12, 0x100
	s_barrier
	s_nop 7
	ds_write2st64_b32 v45, v0, v1 offset1:1
	s_nop 0
	ds_write2st64_b32 v45, v16, v17 offset0:128 offset1:129
	ds_write2st64_b32 v45, v2, v3 offset0:2 offset1:3
	ds_write2st64_b32 v45, v18, v19 offset0:130 offset1:131
	ds_write2st64_b32 v45, v4, v5 offset0:4 offset1:5
	ds_write2st64_b32 v45, v20, v21 offset0:132 offset1:133
	ds_write2st64_b32 v45, v6, v7 offset0:6 offset1:7
	ds_write2st64_b32 v45, v22, v23 offset0:134 offset1:135
	ds_write2st64_b32 v45, v8, v9 offset0:8 offset1:9
	ds_write2st64_b32 v45, v24, v25 offset0:136 offset1:137
	ds_write2st64_b32 v45, v10, v11 offset0:10 offset1:11
	ds_write2st64_b32 v45, v26, v27 offset0:138 offset1:139
	ds_write2st64_b32 v45, v12, v13 offset0:12 offset1:13
	ds_write2st64_b32 v45, v28, v29 offset0:140 offset1:141
	ds_write2st64_b32 v45, v14, v15 offset0:14 offset1:15
	ds_write2st64_b32 v45, v30, v31 offset0:142 offset1:143
	s_waitcnt lgkmcnt(0)
	s_barrier
	ds_read2st64_b32 v[0:1], v44 offset1:1
	ds_read2st64_b32 v[2:3], v44 offset0:16 offset1:17
	ds_read2st64_b32 v[4:5], v44 offset0:32 offset1:33
	ds_read2st64_b32 v[6:7], v44 offset0:48 offset1:49
	ds_read2st64_b32 v[8:9], v44 offset0:128 offset1:129
	ds_read2st64_b32 v[10:11], v44 offset0:144 offset1:145
	ds_read2st64_b32 v[12:13], v44 offset0:160 offset1:161
	ds_read2st64_b32 v[14:15], v44 offset0:176 offset1:177
	ds_read2st64_b32 v[16:17], v44 offset0:64 offset1:65
	ds_read2st64_b32 v[18:19], v44 offset0:80 offset1:81
	ds_read2st64_b32 v[20:21], v44 offset0:96 offset1:97
	ds_read2st64_b32 v[22:23], v44 offset0:112 offset1:113
	ds_read2st64_b32 v[24:25], v44 offset0:192 offset1:193
	ds_read2st64_b32 v[26:27], v44 offset0:208 offset1:209
	ds_read2st64_b32 v[28:29], v44 offset0:224 offset1:225
	ds_read2st64_b32 v[30:31], v44 offset0:240 offset1:241
	s_waitcnt lgkmcnt(11)
	v_mov_b32_e32 v38, v8
	v_mov_b32_e32 v39, v0
	v_pk_add_f32 v[38:39], v[38:39], 0 op_sel_hi:[1,0]
	s_waitcnt lgkmcnt(10)
	v_mov_b32_e32 v40, v10
	v_mov_b32_e32 v41, v2
	v_mov_b32_e32 v0, v9
	v_pk_add_f32 v[38:39], v[38:39], v[40:41]
	s_waitcnt lgkmcnt(9)
	v_mov_b32_e32 v40, v12
	v_mov_b32_e32 v41, v4
	v_pk_add_f32 v[0:1], v[0:1], 0 op_sel_hi:[1,0]
	v_mov_b32_e32 v2, v11
	v_pk_add_f32 v[38:39], v[38:39], v[40:41]
	s_waitcnt lgkmcnt(8)
	v_mov_b32_e32 v40, v14
	v_mov_b32_e32 v41, v6
	v_pk_add_f32 v[0:1], v[0:1], v[2:3]
	v_mov_b32_e32 v4, v13
	v_pk_add_f32 v[38:39], v[38:39], v[40:41]
	s_waitcnt lgkmcnt(3)
	v_mov_b32_e32 v40, v24
	v_mov_b32_e32 v41, v16
	v_pk_add_f32 v[0:1], v[0:1], v[4:5]
	v_mov_b32_e32 v6, v15
	v_pk_add_f32 v[38:39], v[38:39], v[40:41]
	s_waitcnt lgkmcnt(2)
	v_mov_b32_e32 v40, v26
	v_mov_b32_e32 v41, v18
	v_pk_add_f32 v[0:1], v[0:1], v[6:7]
	v_mov_b32_e32 v16, v25
	v_pk_add_f32 v[38:39], v[38:39], v[40:41]
	s_waitcnt lgkmcnt(1)
	v_mov_b32_e32 v40, v28
	v_mov_b32_e32 v41, v20
	v_pk_add_f32 v[0:1], v[0:1], v[16:17]
	v_mov_b32_e32 v18, v27
	v_pk_add_f32 v[38:39], v[38:39], v[40:41]
	s_waitcnt lgkmcnt(0)
	v_mov_b32_e32 v40, v30
	v_mov_b32_e32 v41, v22
	v_pk_add_f32 v[0:1], v[0:1], v[18:19]
	v_mov_b32_e32 v20, v29
	v_pk_add_f32 v[38:39], v[38:39], v[40:41]
	v_pk_add_f32 v[0:1], v[0:1], v[20:21]
	v_mov_b32_e32 v22, v31
	v_pk_add_f32 v[0:1], v[0:1], v[22:23]
	v_mul_f32_e32 v2, 0xbfb8aa3b, v39
	v_exp_f32_e32 v2, v2
	v_mul_f32_e32 v3, 0xbfb8aa3b, v1
	v_exp_f32_e32 v3, v3
	s_lshl_b32 s0, s20, 3
	v_add_f32_e32 v2, 1.0, v2
	v_rcp_f32_e32 v4, v2
	v_add_f32_e32 v2, 1.0, v3
	v_rcp_f32_e32 v3, v2
	s_andn2_b32 s0, s0, 31
	v_mul_f32_e32 v4, v39, v4
	v_mul_f32_e32 v4, v38, v4
	v_mul_f32_e32 v1, v1, v3
	v_mul_f32_e32 v0, v0, v1
	v_cvt_pk_bf16_f32 v4, v4, v0
	v_mov_b64_e32 v[0:1], s[10:11]
	v_add_u32_e32 v2, s0, v43
	v_mad_u64_u32 v[0:1], s[0:1], v36, s16, v[0:1]
	s_add_i32 s0, s19, 1
	s_add_i32 s83, s83, s70
	s_add_i32 s18, s18, s46
	s_add_i32 s17, s17, s71
	v_ashrrev_i32_e32 v3, 31, v2
	s_cmp_gt_u32 s19, 2
	v_lshl_add_u64 v[0:1], v[2:3], 1, v[0:1]
	s_cselect_b64 s[12:13], -1, 0
	s_mov_b32 s19, s0
	global_store_dword v[0:1], v4, off
	s_branch .LBB0_1126
